# static s_setprio 1 for the younger wave half (waves 4-7) across the P2 attention phase (lever: one static priority raise), reset to 0 after
# baseline (speedup 1.0000x reference)
.LBB0_337:
	s_or_b64 exec, exec, s[4:5]
	s_add_u32 s30, s92, 0xa800000
	s_addc_u32 s31, s93, 0
	s_cmpk_lt_i32 s33, 0x100
	s_cselect_b64 s[4:5], -1, 0
	s_cmpk_gt_i32 s33, 0xff
	s_mov_b32 s58, s80
	v_readlane_b32 s59, v239, 2
	s_waitcnt lgkmcnt(0)
	s_barrier
	v_mbcnt_lo_u32_b32 v170, -1, 0
	v_mbcnt_hi_u32_b32 v170, -1, v170
	s_cbranch_scc1 .LBB0_377
	s_mul_i32 s0, s81, 0x1200
	s_add_i32 s74, s0, 0
	s_mov_b32 s11, 0
	s_add_i32 s72, s74, 0x12800
	s_lshl_b32 s73, s81, 1
	s_add_i32 s74, s74, 0x1b800
	s_movk_i32 s75, 0x3000
	v_mov_b32_e32 v145, 0
	s_movk_i32 s76, 0x90
	v_mov_b32_e32 v171, 0xff800000
	s_mov_b32 s77, 0x3e38aa3b
	s_movk_i32 s82, 0x1000
	s_mov_b32 s83, s33
	s_cmp_lt_u32 s81, 4
	s_cbranch_scc1 .Lattn_prio_done
	s_setprio 1
.Lattn_prio_done:
	s_branch .LBB0_340
.LBB0_339:
	v_mbcnt_lo_u32_b32 v0, -1, 0
	v_mbcnt_hi_u32_b32 v0, -1, v0
	s_or_b32 s34, s34, s84
	v_add_u32_e32 v11, s97, v0
	v_lshlrev_b32_e32 v0, 4, v0
	v_ashrrev_i32_e32 v4, 3, v11
	v_and_b32_e32 v144, 0x70, v0
	s_add_u32 s0, s30, s10
	v_ashrrev_i32_e32 v5, 31, v4
	v_add_u32_e32 v10, 0, v144
	s_addc_u32 s1, s31, 0
	v_lshl_add_u64 v[14:15], s[34:35], 0, v[4:5]
	v_mov_b64_e32 v[12:13], s[28:29]
	v_lshl_add_u64 v[8:9], s[0:1], 0, v[144:145]
	v_mad_u64_u32 v[0:1], s[0:1], v4, s76, v[10:11]
	v_mad_u64_u32 v[4:5], s[0:1], v14, s75, v[12:13]
	v_mad_i32_i24 v5, v15, s75, v5
	v_lshl_add_u64 v[4:5], v[4:5], 0, s[10:11]
	v_lshl_add_u64 v[4:5], v[4:5], 0, v[144:145]
	v_add_co_u32_e32 v4, vcc, s82, v4
	s_mov_b32 s14, 0xc0000
	s_mov_b32 s15, 0
	v_addc_co_u32_e32 v5, vcc, 0, v5, vcc
	v_lshlrev_b64 v[6:7], 12, v[14:15]
	v_lshl_add_u64 v[6:7], v[8:9], 0, v[6:7]
	s_mov_b32 s18, 0x40000
	s_mov_b32 s19, 0
	ds_read_b128 v[80:83], v0
	ds_read_b128 v[84:87], v0 offset:9216
	ds_read_b128 v[88:91], v0 offset:18432
	ds_read_b128 v[92:95], v0 offset:27648
	ds_read_b128 v[96:99], v0 offset:36864
	ds_read_b128 v[100:103], v0 offset:46080
	ds_read_b128 v[104:107], v0 offset:55296
	ds_read_b128 v[108:111], v0 offset:64512
	global_load_dwordx4 v[112:115], v[4:5], off offset:2048 nt
	v_lshl_add_u64 v[4:5], v[4:5], 0, s[14:15]
	global_load_dwordx4 v[116:119], v[4:5], off offset:2048 nt
	v_lshl_add_u64 v[4:5], v[4:5], 0, s[14:15]
	global_load_dwordx4 v[120:123], v[4:5], off offset:2048 nt
	v_lshl_add_u64 v[4:5], v[4:5], 0, s[14:15]
	global_load_dwordx4 v[124:127], v[4:5], off offset:2048 nt
	v_lshl_add_u64 v[4:5], v[4:5], 0, s[14:15]
	global_load_dwordx4 v[128:131], v[4:5], off offset:2048 nt
	v_lshl_add_u64 v[4:5], v[4:5], 0, s[14:15]
	global_load_dwordx4 v[132:135], v[4:5], off offset:2048 nt
	v_lshl_add_u64 v[4:5], v[4:5], 0, s[14:15]
	global_load_dwordx4 v[48:51], v[4:5], off offset:2048 nt
	v_lshl_add_u64 v[4:5], v[4:5], 0, s[14:15]
	global_load_dwordx4 v[52:55], v[4:5], off offset:2048 nt
	s_waitcnt lgkmcnt(0)
	s_waitcnt vmcnt(7)
	v_lshlrev_b32_e32 v20, 16, v80
	v_and_b32_e32 v21, 0xffff0000, v80
	v_lshlrev_b32_e32 v16, 16, v112
	v_and_b32_e32 v17, 0xffff0000, v112
	v_mul_f32_e32 v22, 0xbfb8aa3b, v16
	v_mul_f32_e32 v23, 0xbfb8aa3b, v17
	v_exp_f32_e32 v22, v22
	v_exp_f32_e32 v23, v23
	s_nop 0
	v_add_f32_e32 v22, 1.0, v22
	v_add_f32_e32 v23, 1.0, v23
	v_rcp_f32_e32 v18, v22
	v_rcp_f32_e32 v19, v23
	s_nop 1
	v_pk_mul_f32 v[16:17], v[18:19], v[16:17]
	s_nop 0
	v_pk_mul_f32 v[16:17], v[16:17], v[20:21]
	s_nop 0
	v_cvt_pk_bf16_f32 v0, v16, v17
	v_lshlrev_b32_e32 v20, 16, v81
	v_and_b32_e32 v21, 0xffff0000, v81
	v_lshlrev_b32_e32 v16, 16, v113
	v_and_b32_e32 v17, 0xffff0000, v113
	v_mul_f32_e32 v22, 0xbfb8aa3b, v16
	v_mul_f32_e32 v23, 0xbfb8aa3b, v17
	v_exp_f32_e32 v22, v22
	v_exp_f32_e32 v23, v23
	s_nop 0
	v_add_f32_e32 v22, 1.0, v22
	v_add_f32_e32 v23, 1.0, v23
	v_rcp_f32_e32 v18, v22
	v_rcp_f32_e32 v19, v23
	s_nop 1
	v_pk_mul_f32 v[16:17], v[18:19], v[16:17]
	s_nop 0
	v_pk_mul_f32 v[16:17], v[16:17], v[20:21]
	s_nop 0
	v_cvt_pk_bf16_f32 v1, v16, v17
	v_lshlrev_b32_e32 v20, 16, v82
	v_and_b32_e32 v21, 0xffff0000, v82
	v_lshlrev_b32_e32 v16, 16, v114
	v_and_b32_e32 v17, 0xffff0000, v114
	v_mul_f32_e32 v22, 0xbfb8aa3b, v16
	v_mul_f32_e32 v23, 0xbfb8aa3b, v17
	v_exp_f32_e32 v22, v22
	v_exp_f32_e32 v23, v23
	s_nop 0
	v_add_f32_e32 v22, 1.0, v22
	v_add_f32_e32 v23, 1.0, v23
	v_rcp_f32_e32 v18, v22
	v_rcp_f32_e32 v19, v23
	s_nop 1
	v_pk_mul_f32 v[16:17], v[18:19], v[16:17]
	s_nop 0
	v_pk_mul_f32 v[16:17], v[16:17], v[20:21]
	s_nop 0
	v_cvt_pk_bf16_f32 v2, v16, v17
	v_lshlrev_b32_e32 v20, 16, v83
	v_and_b32_e32 v21, 0xffff0000, v83
	v_lshlrev_b32_e32 v16, 16, v115
	v_and_b32_e32 v17, 0xffff0000, v115
	v_mul_f32_e32 v22, 0xbfb8aa3b, v16
	v_mul_f32_e32 v23, 0xbfb8aa3b, v17
	v_exp_f32_e32 v22, v22
	v_exp_f32_e32 v23, v23
	s_nop 0
	v_add_f32_e32 v22, 1.0, v22
	v_add_f32_e32 v23, 1.0, v23
	v_rcp_f32_e32 v18, v22
	v_rcp_f32_e32 v19, v23
	s_nop 1
	v_pk_mul_f32 v[16:17], v[18:19], v[16:17]
	s_nop 0
	v_pk_mul_f32 v[16:17], v[16:17], v[20:21]
	s_nop 0
	v_cvt_pk_bf16_f32 v3, v16, v17
	s_nop 0
	global_store_dwordx4 v[6:7], v[0:3], off
	s_waitcnt vmcnt(7)
	v_lshl_add_u64 v[6:7], v[6:7], 0, s[18:19]
	v_lshlrev_b32_e32 v20, 16, v84
	v_and_b32_e32 v21, 0xffff0000, v84
	v_lshlrev_b32_e32 v16, 16, v116
	v_and_b32_e32 v17, 0xffff0000, v116
	v_mul_f32_e32 v22, 0xbfb8aa3b, v16
	v_mul_f32_e32 v23, 0xbfb8aa3b, v17
	v_exp_f32_e32 v22, v22
	v_exp_f32_e32 v23, v23
	s_nop 0
	v_add_f32_e32 v22, 1.0, v22
	v_add_f32_e32 v23, 1.0, v23
	v_rcp_f32_e32 v18, v22
	v_rcp_f32_e32 v19, v23
	s_nop 1
	v_pk_mul_f32 v[16:17], v[18:19], v[16:17]
	s_nop 0
	v_pk_mul_f32 v[16:17], v[16:17], v[20:21]
	s_nop 0
	v_cvt_pk_bf16_f32 v24, v16, v17
	v_lshlrev_b32_e32 v20, 16, v85
	v_and_b32_e32 v21, 0xffff0000, v85
	v_lshlrev_b32_e32 v16, 16, v117
	v_and_b32_e32 v17, 0xffff0000, v117
	v_mul_f32_e32 v22, 0xbfb8aa3b, v16
	v_mul_f32_e32 v23, 0xbfb8aa3b, v17
	v_exp_f32_e32 v22, v22
	v_exp_f32_e32 v23, v23
	s_nop 0
	v_add_f32_e32 v22, 1.0, v22
	v_add_f32_e32 v23, 1.0, v23
	v_rcp_f32_e32 v18, v22
	v_rcp_f32_e32 v19, v23
	s_nop 1
	v_pk_mul_f32 v[16:17], v[18:19], v[16:17]
	s_nop 0
	v_pk_mul_f32 v[16:17], v[16:17], v[20:21]
	s_nop 0
	v_cvt_pk_bf16_f32 v25, v16, v17
	v_lshlrev_b32_e32 v20, 16, v86
	v_and_b32_e32 v21, 0xffff0000, v86
	v_lshlrev_b32_e32 v16, 16, v118
	v_and_b32_e32 v17, 0xffff0000, v118
	v_mul_f32_e32 v22, 0xbfb8aa3b, v16
	v_mul_f32_e32 v23, 0xbfb8aa3b, v17
	v_exp_f32_e32 v22, v22
	v_exp_f32_e32 v23, v23
	s_nop 0
	v_add_f32_e32 v22, 1.0, v22
	v_add_f32_e32 v23, 1.0, v23
	v_rcp_f32_e32 v18, v22
	v_rcp_f32_e32 v19, v23
	s_nop 1
	v_pk_mul_f32 v[16:17], v[18:19], v[16:17]
	s_nop 0
	v_pk_mul_f32 v[16:17], v[16:17], v[20:21]
	s_nop 0
	v_cvt_pk_bf16_f32 v26, v16, v17
	v_lshlrev_b32_e32 v20, 16, v87
	v_and_b32_e32 v21, 0xffff0000, v87
	v_lshlrev_b32_e32 v16, 16, v119
	v_and_b32_e32 v17, 0xffff0000, v119
	v_mul_f32_e32 v22, 0xbfb8aa3b, v16
	v_mul_f32_e32 v23, 0xbfb8aa3b, v17
	v_exp_f32_e32 v22, v22
	v_exp_f32_e32 v23, v23
	s_nop 0
	v_add_f32_e32 v22, 1.0, v22
	v_add_f32_e32 v23, 1.0, v23
	v_rcp_f32_e32 v18, v22
	v_rcp_f32_e32 v19, v23
	s_nop 1
	v_pk_mul_f32 v[16:17], v[18:19], v[16:17]
	s_nop 0
	v_pk_mul_f32 v[16:17], v[16:17], v[20:21]
	s_nop 0
	v_cvt_pk_bf16_f32 v27, v16, v17
	s_nop 0
	global_store_dwordx4 v[6:7], v[24:27], off
	s_waitcnt vmcnt(7)
	v_lshl_add_u64 v[6:7], v[6:7], 0, s[18:19]
	v_lshlrev_b32_e32 v20, 16, v88
	v_and_b32_e32 v21, 0xffff0000, v88
	v_lshlrev_b32_e32 v16, 16, v120
	v_and_b32_e32 v17, 0xffff0000, v120
	v_mul_f32_e32 v22, 0xbfb8aa3b, v16
	v_mul_f32_e32 v23, 0xbfb8aa3b, v17
	v_exp_f32_e32 v22, v22
	v_exp_f32_e32 v23, v23
	s_nop 0
	v_add_f32_e32 v22, 1.0, v22
	v_add_f32_e32 v23, 1.0, v23
	v_rcp_f32_e32 v18, v22
	v_rcp_f32_e32 v19, v23
	s_nop 1
	v_pk_mul_f32 v[16:17], v[18:19], v[16:17]
	s_nop 0
	v_pk_mul_f32 v[16:17], v[16:17], v[20:21]
	s_nop 0
	v_cvt_pk_bf16_f32 v0, v16, v17
	v_lshlrev_b32_e32 v20, 16, v89
	v_and_b32_e32 v21, 0xffff0000, v89
	v_lshlrev_b32_e32 v16, 16, v121
	v_and_b32_e32 v17, 0xffff0000, v121
	v_mul_f32_e32 v22, 0xbfb8aa3b, v16
	v_mul_f32_e32 v23, 0xbfb8aa3b, v17
	v_exp_f32_e32 v22, v22
	v_exp_f32_e32 v23, v23
	s_nop 0
	v_add_f32_e32 v22, 1.0, v22
	v_add_f32_e32 v23, 1.0, v23
	v_rcp_f32_e32 v18, v22
	v_rcp_f32_e32 v19, v23
	s_nop 1
	v_pk_mul_f32 v[16:17], v[18:19], v[16:17]
	s_nop 0
	v_pk_mul_f32 v[16:17], v[16:17], v[20:21]
	s_nop 0
	v_cvt_pk_bf16_f32 v1, v16, v17
	v_lshlrev_b32_e32 v20, 16, v90
	v_and_b32_e32 v21, 0xffff0000, v90
	v_lshlrev_b32_e32 v16, 16, v122
	v_and_b32_e32 v17, 0xffff0000, v122
	v_mul_f32_e32 v22, 0xbfb8aa3b, v16
	v_mul_f32_e32 v23, 0xbfb8aa3b, v17
	v_exp_f32_e32 v22, v22
	v_exp_f32_e32 v23, v23
	s_nop 0
	v_add_f32_e32 v22, 1.0, v22
	v_add_f32_e32 v23, 1.0, v23
	v_rcp_f32_e32 v18, v22
	v_rcp_f32_e32 v19, v23
	s_nop 1
	v_pk_mul_f32 v[16:17], v[18:19], v[16:17]
	s_nop 0
	v_pk_mul_f32 v[16:17], v[16:17], v[20:21]
	s_nop 0
	v_cvt_pk_bf16_f32 v2, v16, v17
	v_lshlrev_b32_e32 v20, 16, v91
	v_and_b32_e32 v21, 0xffff0000, v91
	v_lshlrev_b32_e32 v16, 16, v123
	v_and_b32_e32 v17, 0xffff0000, v123
	v_mul_f32_e32 v22, 0xbfb8aa3b, v16
	v_mul_f32_e32 v23, 0xbfb8aa3b, v17
	v_exp_f32_e32 v22, v22
	v_exp_f32_e32 v23, v23
	s_nop 0
	v_add_f32_e32 v22, 1.0, v22
	v_add_f32_e32 v23, 1.0, v23
	v_rcp_f32_e32 v18, v22
	v_rcp_f32_e32 v19, v23
	s_nop 1
	v_pk_mul_f32 v[16:17], v[18:19], v[16:17]
	s_nop 0
	v_pk_mul_f32 v[16:17], v[16:17], v[20:21]
	s_nop 0
	v_cvt_pk_bf16_f32 v3, v16, v17
	s_nop 0
	global_store_dwordx4 v[6:7], v[0:3], off
	s_waitcnt vmcnt(7)
	v_lshl_add_u64 v[6:7], v[6:7], 0, s[18:19]
	v_lshlrev_b32_e32 v20, 16, v92
	v_and_b32_e32 v21, 0xffff0000, v92
	v_lshlrev_b32_e32 v16, 16, v124
	v_and_b32_e32 v17, 0xffff0000, v124
	v_mul_f32_e32 v22, 0xbfb8aa3b, v16
	v_mul_f32_e32 v23, 0xbfb8aa3b, v17
	v_exp_f32_e32 v22, v22
	v_exp_f32_e32 v23, v23
	s_nop 0
	v_add_f32_e32 v22, 1.0, v22
	v_add_f32_e32 v23, 1.0, v23
	v_rcp_f32_e32 v18, v22
	v_rcp_f32_e32 v19, v23
	s_nop 1
	v_pk_mul_f32 v[16:17], v[18:19], v[16:17]
	s_nop 0
	v_pk_mul_f32 v[16:17], v[16:17], v[20:21]
	s_nop 0
	v_cvt_pk_bf16_f32 v24, v16, v17
	v_lshlrev_b32_e32 v20, 16, v93
	v_and_b32_e32 v21, 0xffff0000, v93
	v_lshlrev_b32_e32 v16, 16, v125
	v_and_b32_e32 v17, 0xffff0000, v125
	v_mul_f32_e32 v22, 0xbfb8aa3b, v16
	v_mul_f32_e32 v23, 0xbfb8aa3b, v17
	v_exp_f32_e32 v22, v22
	v_exp_f32_e32 v23, v23
	s_nop 0
	v_add_f32_e32 v22, 1.0, v22
	v_add_f32_e32 v23, 1.0, v23
	v_rcp_f32_e32 v18, v22
	v_rcp_f32_e32 v19, v23
	s_nop 1
	v_pk_mul_f32 v[16:17], v[18:19], v[16:17]
	s_nop 0
	v_pk_mul_f32 v[16:17], v[16:17], v[20:21]
	s_nop 0
	v_cvt_pk_bf16_f32 v25, v16, v17
	v_lshlrev_b32_e32 v20, 16, v94
	v_and_b32_e32 v21, 0xffff0000, v94
	v_lshlrev_b32_e32 v16, 16, v126
	v_and_b32_e32 v17, 0xffff0000, v126
	v_mul_f32_e32 v22, 0xbfb8aa3b, v16
	v_mul_f32_e32 v23, 0xbfb8aa3b, v17
	v_exp_f32_e32 v22, v22
	v_exp_f32_e32 v23, v23
	s_nop 0
	v_add_f32_e32 v22, 1.0, v22
	v_add_f32_e32 v23, 1.0, v23
	v_rcp_f32_e32 v18, v22
	v_rcp_f32_e32 v19, v23
	s_nop 1
	v_pk_mul_f32 v[16:17], v[18:19], v[16:17]
	s_nop 0
	v_pk_mul_f32 v[16:17], v[16:17], v[20:21]
	s_nop 0
	v_cvt_pk_bf16_f32 v26, v16, v17
	v_lshlrev_b32_e32 v20, 16, v95
	v_and_b32_e32 v21, 0xffff0000, v95
	v_lshlrev_b32_e32 v16, 16, v127
	v_and_b32_e32 v17, 0xffff0000, v127
	v_mul_f32_e32 v22, 0xbfb8aa3b, v16
	v_mul_f32_e32 v23, 0xbfb8aa3b, v17
	v_exp_f32_e32 v22, v22
	v_exp_f32_e32 v23, v23
	s_nop 0
	v_add_f32_e32 v22, 1.0, v22
	v_add_f32_e32 v23, 1.0, v23
	v_rcp_f32_e32 v18, v22
	v_rcp_f32_e32 v19, v23
	s_nop 1
	v_pk_mul_f32 v[16:17], v[18:19], v[16:17]
	s_nop 0
	v_pk_mul_f32 v[16:17], v[16:17], v[20:21]
	s_nop 0
	v_cvt_pk_bf16_f32 v27, v16, v17
	s_nop 0
	global_store_dwordx4 v[6:7], v[24:27], off
	s_waitcnt vmcnt(7)
	v_lshl_add_u64 v[6:7], v[6:7], 0, s[18:19]
	v_lshlrev_b32_e32 v20, 16, v96
	v_and_b32_e32 v21, 0xffff0000, v96
	v_lshlrev_b32_e32 v16, 16, v128
	v_and_b32_e32 v17, 0xffff0000, v128
	v_mul_f32_e32 v22, 0xbfb8aa3b, v16
	v_mul_f32_e32 v23, 0xbfb8aa3b, v17
	v_exp_f32_e32 v22, v22
	v_exp_f32_e32 v23, v23
	s_nop 0
	v_add_f32_e32 v22, 1.0, v22
	v_add_f32_e32 v23, 1.0, v23
	v_rcp_f32_e32 v18, v22
	v_rcp_f32_e32 v19, v23
	s_nop 1
	v_pk_mul_f32 v[16:17], v[18:19], v[16:17]
	s_nop 0
	v_pk_mul_f32 v[16:17], v[16:17], v[20:21]
	s_nop 0
	v_cvt_pk_bf16_f32 v0, v16, v17
	v_lshlrev_b32_e32 v20, 16, v97
	v_and_b32_e32 v21, 0xffff0000, v97
	v_lshlrev_b32_e32 v16, 16, v129
	v_and_b32_e32 v17, 0xffff0000, v129
	v_mul_f32_e32 v22, 0xbfb8aa3b, v16
	v_mul_f32_e32 v23, 0xbfb8aa3b, v17
	v_exp_f32_e32 v22, v22
	v_exp_f32_e32 v23, v23
	s_nop 0
	v_add_f32_e32 v22, 1.0, v22
	v_add_f32_e32 v23, 1.0, v23
	v_rcp_f32_e32 v18, v22
	v_rcp_f32_e32 v19, v23
	s_nop 1
	v_pk_mul_f32 v[16:17], v[18:19], v[16:17]
	s_nop 0
	v_pk_mul_f32 v[16:17], v[16:17], v[20:21]
	s_nop 0
	v_cvt_pk_bf16_f32 v1, v16, v17
	v_lshlrev_b32_e32 v20, 16, v98
	v_and_b32_e32 v21, 0xffff0000, v98
	v_lshlrev_b32_e32 v16, 16, v130
	v_and_b32_e32 v17, 0xffff0000, v130
	v_mul_f32_e32 v22, 0xbfb8aa3b, v16
	v_mul_f32_e32 v23, 0xbfb8aa3b, v17
	v_exp_f32_e32 v22, v22
	v_exp_f32_e32 v23, v23
	s_nop 0
	v_add_f32_e32 v22, 1.0, v22
	v_add_f32_e32 v23, 1.0, v23
	v_rcp_f32_e32 v18, v22
	v_rcp_f32_e32 v19, v23
	s_nop 1
	v_pk_mul_f32 v[16:17], v[18:19], v[16:17]
	s_nop 0
	v_pk_mul_f32 v[16:17], v[16:17], v[20:21]
	s_nop 0
	v_cvt_pk_bf16_f32 v2, v16, v17
	v_lshlrev_b32_e32 v20, 16, v99
	v_and_b32_e32 v21, 0xffff0000, v99
	v_lshlrev_b32_e32 v16, 16, v131
	v_and_b32_e32 v17, 0xffff0000, v131
	v_mul_f32_e32 v22, 0xbfb8aa3b, v16
	v_mul_f32_e32 v23, 0xbfb8aa3b, v17
	v_exp_f32_e32 v22, v22
	v_exp_f32_e32 v23, v23
	s_nop 0
	v_add_f32_e32 v22, 1.0, v22
	v_add_f32_e32 v23, 1.0, v23
	v_rcp_f32_e32 v18, v22
	v_rcp_f32_e32 v19, v23
	s_nop 1
	v_pk_mul_f32 v[16:17], v[18:19], v[16:17]
	s_nop 0
	v_pk_mul_f32 v[16:17], v[16:17], v[20:21]
	s_nop 0
	v_cvt_pk_bf16_f32 v3, v16, v17
	s_nop 0
	global_store_dwordx4 v[6:7], v[0:3], off
	s_waitcnt vmcnt(7)
	v_lshl_add_u64 v[6:7], v[6:7], 0, s[18:19]
	v_lshlrev_b32_e32 v20, 16, v100
	v_and_b32_e32 v21, 0xffff0000, v100
	v_lshlrev_b32_e32 v16, 16, v132
	v_and_b32_e32 v17, 0xffff0000, v132
	v_mul_f32_e32 v22, 0xbfb8aa3b, v16
	v_mul_f32_e32 v23, 0xbfb8aa3b, v17
	v_exp_f32_e32 v22, v22
	v_exp_f32_e32 v23, v23
	s_nop 0
	v_add_f32_e32 v22, 1.0, v22
	v_add_f32_e32 v23, 1.0, v23
	v_rcp_f32_e32 v18, v22
	v_rcp_f32_e32 v19, v23
	s_nop 1
	v_pk_mul_f32 v[16:17], v[18:19], v[16:17]
	s_nop 0
	v_pk_mul_f32 v[16:17], v[16:17], v[20:21]
	s_nop 0
	v_cvt_pk_bf16_f32 v24, v16, v17
	v_lshlrev_b32_e32 v20, 16, v101
	v_and_b32_e32 v21, 0xffff0000, v101
	v_lshlrev_b32_e32 v16, 16, v133
	v_and_b32_e32 v17, 0xffff0000, v133
	v_mul_f32_e32 v22, 0xbfb8aa3b, v16
	v_mul_f32_e32 v23, 0xbfb8aa3b, v17
	v_exp_f32_e32 v22, v22
	v_exp_f32_e32 v23, v23
	s_nop 0
	v_add_f32_e32 v22, 1.0, v22
	v_add_f32_e32 v23, 1.0, v23
	v_rcp_f32_e32 v18, v22
	v_rcp_f32_e32 v19, v23
	s_nop 1
	v_pk_mul_f32 v[16:17], v[18:19], v[16:17]
	s_nop 0
	v_pk_mul_f32 v[16:17], v[16:17], v[20:21]
	s_nop 0
	v_cvt_pk_bf16_f32 v25, v16, v17
	v_lshlrev_b32_e32 v20, 16, v102
	v_and_b32_e32 v21, 0xffff0000, v102
	v_lshlrev_b32_e32 v16, 16, v134
	v_and_b32_e32 v17, 0xffff0000, v134
	v_mul_f32_e32 v22, 0xbfb8aa3b, v16
	v_mul_f32_e32 v23, 0xbfb8aa3b, v17
	v_exp_f32_e32 v22, v22
	v_exp_f32_e32 v23, v23
	s_nop 0
	v_add_f32_e32 v22, 1.0, v22
	v_add_f32_e32 v23, 1.0, v23
	v_rcp_f32_e32 v18, v22
	v_rcp_f32_e32 v19, v23
	s_nop 1
	v_pk_mul_f32 v[16:17], v[18:19], v[16:17]
	s_nop 0
	v_pk_mul_f32 v[16:17], v[16:17], v[20:21]
	s_nop 0
	v_cvt_pk_bf16_f32 v26, v16, v17
	v_lshlrev_b32_e32 v20, 16, v103
	v_and_b32_e32 v21, 0xffff0000, v103
	v_lshlrev_b32_e32 v16, 16, v135
	v_and_b32_e32 v17, 0xffff0000, v135
	v_mul_f32_e32 v22, 0xbfb8aa3b, v16
	v_mul_f32_e32 v23, 0xbfb8aa3b, v17
	v_exp_f32_e32 v22, v22
	v_exp_f32_e32 v23, v23
	s_nop 0
	v_add_f32_e32 v22, 1.0, v22
	v_add_f32_e32 v23, 1.0, v23
	v_rcp_f32_e32 v18, v22
	v_rcp_f32_e32 v19, v23
	s_nop 1
	v_pk_mul_f32 v[16:17], v[18:19], v[16:17]
	s_nop 0
	v_pk_mul_f32 v[16:17], v[16:17], v[20:21]
	s_nop 0
	v_cvt_pk_bf16_f32 v27, v16, v17
	s_nop 0
	global_store_dwordx4 v[6:7], v[24:27], off
	s_waitcnt vmcnt(7)
	v_lshl_add_u64 v[6:7], v[6:7], 0, s[18:19]
	v_lshlrev_b32_e32 v20, 16, v104
	v_and_b32_e32 v21, 0xffff0000, v104
	v_lshlrev_b32_e32 v16, 16, v48
	v_and_b32_e32 v17, 0xffff0000, v48
	v_mul_f32_e32 v22, 0xbfb8aa3b, v16
	v_mul_f32_e32 v23, 0xbfb8aa3b, v17
	v_exp_f32_e32 v22, v22
	v_exp_f32_e32 v23, v23
	s_nop 0
	v_add_f32_e32 v22, 1.0, v22
	v_add_f32_e32 v23, 1.0, v23
	v_rcp_f32_e32 v18, v22
	v_rcp_f32_e32 v19, v23
	s_nop 1
	v_pk_mul_f32 v[16:17], v[18:19], v[16:17]
	s_nop 0
	v_pk_mul_f32 v[16:17], v[16:17], v[20:21]
	s_nop 0
	v_cvt_pk_bf16_f32 v0, v16, v17
	v_lshlrev_b32_e32 v20, 16, v105
	v_and_b32_e32 v21, 0xffff0000, v105
	v_lshlrev_b32_e32 v16, 16, v49
	v_and_b32_e32 v17, 0xffff0000, v49
	v_mul_f32_e32 v22, 0xbfb8aa3b, v16
	v_mul_f32_e32 v23, 0xbfb8aa3b, v17
	v_exp_f32_e32 v22, v22
	v_exp_f32_e32 v23, v23
	s_nop 0
	v_add_f32_e32 v22, 1.0, v22
	v_add_f32_e32 v23, 1.0, v23
	v_rcp_f32_e32 v18, v22
	v_rcp_f32_e32 v19, v23
	s_nop 1
	v_pk_mul_f32 v[16:17], v[18:19], v[16:17]
	s_nop 0
	v_pk_mul_f32 v[16:17], v[16:17], v[20:21]
	s_nop 0
	v_cvt_pk_bf16_f32 v1, v16, v17
	v_lshlrev_b32_e32 v20, 16, v106
	v_and_b32_e32 v21, 0xffff0000, v106
	v_lshlrev_b32_e32 v16, 16, v50
	v_and_b32_e32 v17, 0xffff0000, v50
	v_mul_f32_e32 v22, 0xbfb8aa3b, v16
	v_mul_f32_e32 v23, 0xbfb8aa3b, v17
	v_exp_f32_e32 v22, v22
	v_exp_f32_e32 v23, v23
	s_nop 0
	v_add_f32_e32 v22, 1.0, v22
	v_add_f32_e32 v23, 1.0, v23
	v_rcp_f32_e32 v18, v22
	v_rcp_f32_e32 v19, v23
	s_nop 1
	v_pk_mul_f32 v[16:17], v[18:19], v[16:17]
	s_nop 0
	v_pk_mul_f32 v[16:17], v[16:17], v[20:21]
	s_nop 0
	v_cvt_pk_bf16_f32 v2, v16, v17
	v_lshlrev_b32_e32 v20, 16, v107
	v_and_b32_e32 v21, 0xffff0000, v107
	v_lshlrev_b32_e32 v16, 16, v51
	v_and_b32_e32 v17, 0xffff0000, v51
	v_mul_f32_e32 v22, 0xbfb8aa3b, v16
	v_mul_f32_e32 v23, 0xbfb8aa3b, v17
	v_exp_f32_e32 v22, v22
	v_exp_f32_e32 v23, v23
	s_nop 0
	v_add_f32_e32 v22, 1.0, v22
	v_add_f32_e32 v23, 1.0, v23
	v_rcp_f32_e32 v18, v22
	v_rcp_f32_e32 v19, v23
	s_nop 1
	v_pk_mul_f32 v[16:17], v[18:19], v[16:17]
	s_nop 0
	v_pk_mul_f32 v[16:17], v[16:17], v[20:21]
	s_nop 0
	v_cvt_pk_bf16_f32 v3, v16, v17
	s_nop 0
	global_store_dwordx4 v[6:7], v[0:3], off
	s_waitcnt vmcnt(7)
	v_lshl_add_u64 v[6:7], v[6:7], 0, s[18:19]
	v_lshlrev_b32_e32 v20, 16, v108
	v_and_b32_e32 v21, 0xffff0000, v108
	v_lshlrev_b32_e32 v16, 16, v52
	v_and_b32_e32 v17, 0xffff0000, v52
	v_mul_f32_e32 v22, 0xbfb8aa3b, v16
	v_mul_f32_e32 v23, 0xbfb8aa3b, v17
	v_exp_f32_e32 v22, v22
	v_exp_f32_e32 v23, v23
	s_nop 0
	v_add_f32_e32 v22, 1.0, v22
	v_add_f32_e32 v23, 1.0, v23
	v_rcp_f32_e32 v18, v22
	v_rcp_f32_e32 v19, v23
	s_nop 1
	v_pk_mul_f32 v[16:17], v[18:19], v[16:17]
	s_nop 0
	v_pk_mul_f32 v[16:17], v[16:17], v[20:21]
	s_nop 0
	v_cvt_pk_bf16_f32 v24, v16, v17
	v_lshlrev_b32_e32 v20, 16, v109
	v_and_b32_e32 v21, 0xffff0000, v109
	v_lshlrev_b32_e32 v16, 16, v53
	v_and_b32_e32 v17, 0xffff0000, v53
	v_mul_f32_e32 v22, 0xbfb8aa3b, v16
	v_mul_f32_e32 v23, 0xbfb8aa3b, v17
	v_exp_f32_e32 v22, v22
	v_exp_f32_e32 v23, v23
	s_nop 0
	v_add_f32_e32 v22, 1.0, v22
	v_add_f32_e32 v23, 1.0, v23
	v_rcp_f32_e32 v18, v22
	v_rcp_f32_e32 v19, v23
	s_nop 1
	v_pk_mul_f32 v[16:17], v[18:19], v[16:17]
	s_nop 0
	v_pk_mul_f32 v[16:17], v[16:17], v[20:21]
	s_nop 0
	v_cvt_pk_bf16_f32 v25, v16, v17
	v_lshlrev_b32_e32 v20, 16, v110
	v_and_b32_e32 v21, 0xffff0000, v110
	v_lshlrev_b32_e32 v16, 16, v54
	v_and_b32_e32 v17, 0xffff0000, v54
	v_mul_f32_e32 v22, 0xbfb8aa3b, v16
	v_mul_f32_e32 v23, 0xbfb8aa3b, v17
	v_exp_f32_e32 v22, v22
	v_exp_f32_e32 v23, v23
	s_nop 0
	v_add_f32_e32 v22, 1.0, v22
	v_add_f32_e32 v23, 1.0, v23
	v_rcp_f32_e32 v18, v22
	v_rcp_f32_e32 v19, v23
	s_nop 1
	v_pk_mul_f32 v[16:17], v[18:19], v[16:17]
	s_nop 0
	v_pk_mul_f32 v[16:17], v[16:17], v[20:21]
	s_nop 0
	v_cvt_pk_bf16_f32 v26, v16, v17
	v_lshlrev_b32_e32 v20, 16, v111
	v_and_b32_e32 v21, 0xffff0000, v111
	v_lshlrev_b32_e32 v16, 16, v55
	v_and_b32_e32 v17, 0xffff0000, v55
	v_mul_f32_e32 v22, 0xbfb8aa3b, v16
	v_mul_f32_e32 v23, 0xbfb8aa3b, v17
	v_exp_f32_e32 v22, v22
	v_exp_f32_e32 v23, v23
	s_nop 0
	v_add_f32_e32 v22, 1.0, v22
	v_add_f32_e32 v23, 1.0, v23
	v_rcp_f32_e32 v18, v22
	v_rcp_f32_e32 v19, v23
	s_nop 1
	v_pk_mul_f32 v[16:17], v[18:19], v[16:17]
	s_nop 0
	v_pk_mul_f32 v[16:17], v[16:17], v[20:21]
	s_nop 0
	v_cvt_pk_bf16_f32 v27, v16, v17
	s_nop 0
	global_store_dwordx4 v[6:7], v[24:27], off
	s_add_i32 s83, s83, s94
	s_cmpk_gt_i32 s83, 0xff
	s_barrier
	s_cbranch_scc1 .LBB0_377

.LBB0_377:
	s_setprio 0
	s_add_u32 s14, s92, 0x1a00000
	s_addc_u32 s15, s93, 0
	s_cmpk_gt_i32 s58, 0x7ff
	v_lshlrev_b32_e32 v132, 4, v170
	s_cbranch_scc1 .LBB0_380
	s_lshl_b32 s0, s81, 14
	s_add_i32 s0, s0, 0
	v_and_b32_e32 v2, 0x70, v132
	v_mov_b32_e32 v3, 0
	v_bfe_u32 v4, v170, 3, 3
	v_lshl_add_u64 v[0:1], s[62:63], 0, v[2:3]
	v_add_u32_e32 v6, s0, v2
	v_lshlrev_b32_e32 v2, 3, v170
	v_mul_u32_u24_e32 v7, 0x84, v4
	v_and_b32_e32 v2, 56, v2
	v_mul_u32_u24_e32 v5, 0x84, v2
	v_lshlrev_b32_e32 v2, 1, v2
	v_lshlrev_b32_e32 v8, 2, v4
	v_add_u32_e32 v6, v6, v7
	v_lshl_add_u64 v[2:3], s[14:15], 0, v[2:3]
	v_add3_u32 v5, s0, v5, v8
	s_lshl_b32 s0, s58, 5
	s_lshl_b32 s1, s70, 5
	v_add_u32_e32 v7, 0x420, v6
	v_add_u32_e32 v8, 0x428, v6
	v_add_u32_e32 v9, 0x840, v6
	v_add_u32_e32 v10, 0x848, v6
	v_add_u32_e32 v11, 0xc60, v6
	v_add_u32_e32 v12, 0xc68, v6
	v_add_u32_e32 v13, 0x1080, v6
	v_add_u32_e32 v14, 0x1088, v6
	v_add_u32_e32 v15, 0x14a0, v6
	v_add_u32_e32 v16, 0x14a8, v6
	v_add_u32_e32 v17, 0x18c0, v6
	v_add_u32_e32 v18, 0x18c8, v6
	v_add_u32_e32 v19, 0x1ce0, v6
	v_add_u32_e32 v20, 0x1ce8, v6
